# DA: per-unit bias/delta/subln tables are rebuilt only when the unit's head index changes (they depend on head and layer only and live in an LDS region no unit overwrites)
# speedup vs baseline: 1.0430x; 1.0079x over previous
; __global__ void __launch_bounds__(512, 2) fwd_megakernel(Args a) {
;     ...
;             int lz = l, lanez = threadIdx.x; asm volatile("" : "+s"(lz), "+v"(lanez)); lanez &= 63;
;             const float li = 0.8f - 0.6f * expf(-0.3f * (float)lz);
;             const float p1 = wave_sum(a.lq1[lz * 64 + lanez] * a.lk1[lz * 64 + lanez]), p2 = wave_sum(a.lq2[lz * 64 + lanez] * a.lk2[lz * 64 + lanez]);
;             const float lam = __uint_as_float(__builtin_amdgcn_readfirstlane(__float_as_uint(expf(p1) - expf(p2) + li)));
;             const int vcuz = vcu + (lz - l);
;             for (int u = vcuz; u < 2048; u += G) att::da_unit(lds, proj, yb, u, a.t5, lam, __uint_as_float(__builtin_amdgcn_readfirstlane(__float_as_uint(1.0f - li))), a.subg + lz * 128);
.LBB0_147:
	s_andn2_b64 vcc, exec, s[30:31]
	s_cbranch_vccnz .LBB0_295
	s_mov_b32 s101, -1
	s_mov_b32 s74, s71
	v_mov_b32_e32 v0, v204
	s_mov_b32 s0, 0x3fb8aa3b
	v_cvt_f32_i32_e32 v1, s74
	s_mov_b32 s1, 0xc2ce8ed0
	s_mov_b32 s4, 0x42b17218
	v_and_b32_e32 v0, 63, v0
	v_mul_f32_e32 v1, 0xbe99999a, v1
	v_mul_f32_e32 v2, 0x3fb8aa3b, v1
	v_fma_f32 v3, v1, s0, -v2
	v_rndne_f32_e32 v4, v2
	v_fmac_f32_e32 v3, 0x32a5705f, v1
	v_sub_f32_e32 v2, v2, v4
	v_add_f32_e32 v2, v2, v3
	v_exp_f32_e32 v2, v2
	v_cvt_i32_f32_e32 v3, v4
	v_cmp_ngt_f32_e32 vcc, s1, v1
	v_lshl_or_b32 v0, s74, 6, v0
	v_readlane_b32 s76, v249, 5
	v_ldexp_f32 v2, v2, v3
	v_cndmask_b32_e32 v2, 0, v2, vcc
	v_cmp_nlt_f32_e32 vcc, s4, v1
	v_readlane_b32 s80, v249, 9
	v_readlane_b32 s81, v249, 10
	v_cndmask_b32_e32 v1, v210, v2, vcc
	v_fmamk_f32 v222, v1, 0xbf19999a, v208
	v_ashrrev_i32_e32 v1, 31, v0
	v_readlane_b32 s82, v249, 11
	v_readlane_b32 s83, v249, 12
	v_readlane_b32 s84, v249, 13
	v_readlane_b32 s85, v249, 14
	v_readlane_b32 s86, v249, 15
	v_readlane_b32 s87, v249, 16
	v_lshlrev_b64 v[0:1], 2, v[0:1]
	v_readlane_b32 s88, v249, 17
	v_readlane_b32 s89, v249, 18
	v_readlane_b32 s90, v249, 19
	v_readlane_b32 s91, v249, 20
	s_mov_b64 s[80:81], s[84:85]
	s_mov_b64 s[82:83], s[86:87]
	v_lshl_add_u64 v[2:3], s[80:81], 0, v[0:1]
	global_load_dword v4, v[2:3], off
	v_lshl_add_u64 v[2:3], s[82:83], 0, v[0:1]
	global_load_dword v2, v[2:3], off
	v_and_b32_e32 v5, 64, v205
	v_add_u32_e32 v5, 64, v5
	v_xor_b32_e32 v6, 1, v205
	v_cmp_lt_i32_e32 vcc, v6, v5
	s_mov_b64 s[84:85], s[88:89]
	s_mov_b64 s[86:87], s[90:91]
	v_cndmask_b32_e32 v6, v205, v6, vcc
	v_lshlrev_b32_e32 v6, 2, v6
	s_mov_b32 s12, s13
	v_readlane_b32 s77, v249, 6
	v_readlane_b32 s78, v249, 7
	v_readlane_b32 s79, v249, 8
	s_waitcnt vmcnt(0)
	v_mul_f32_e32 v3, v4, v2
	ds_bpermute_b32 v3, v6, v3
	s_waitcnt lgkmcnt(0)
	v_fmac_f32_e32 v3, v4, v2
	v_xor_b32_e32 v2, 2, v205
	v_cmp_lt_i32_e32 vcc, v2, v5
	s_nop 1
	v_cndmask_b32_e32 v2, v205, v2, vcc
	v_lshlrev_b32_e32 v4, 2, v2
	ds_bpermute_b32 v2, v4, v3
	s_waitcnt lgkmcnt(0)
	v_add_f32_e32 v2, v3, v2
	v_xor_b32_e32 v3, 4, v205
	v_cmp_lt_i32_e32 vcc, v3, v5
	s_nop 1
	v_cndmask_b32_e32 v3, v205, v3, vcc
	v_lshlrev_b32_e32 v7, 2, v3
	ds_bpermute_b32 v3, v7, v2
	s_waitcnt lgkmcnt(0)
	v_add_f32_e32 v2, v2, v3
	v_xor_b32_e32 v3, 8, v205
	v_cmp_lt_i32_e32 vcc, v3, v5
	s_nop 1
	v_cndmask_b32_e32 v3, v205, v3, vcc
	v_lshlrev_b32_e32 v8, 2, v3
	ds_bpermute_b32 v3, v8, v2
	s_waitcnt lgkmcnt(0)
	v_add_f32_e32 v2, v2, v3
	v_xor_b32_e32 v3, 16, v205
	v_cmp_lt_i32_e32 vcc, v3, v5
	s_nop 1
	v_cndmask_b32_e32 v3, v205, v3, vcc
	v_lshlrev_b32_e32 v9, 2, v3
	ds_bpermute_b32 v3, v9, v2
	s_waitcnt lgkmcnt(0)
	v_add_f32_e32 v2, v2, v3
	v_xor_b32_e32 v3, 32, v205
	v_cmp_lt_i32_e32 vcc, v3, v5
	s_nop 1
	v_cndmask_b32_e32 v3, v205, v3, vcc
	v_lshlrev_b32_e32 v5, 2, v3
	ds_bpermute_b32 v3, v5, v2
	s_waitcnt lgkmcnt(0)
	v_add_f32_e32 v10, v2, v3
	v_lshl_add_u64 v[2:3], s[84:85], 0, v[0:1]
	v_lshl_add_u64 v[0:1], s[86:87], 0, v[0:1]
	global_load_dword v2, v[2:3], off
	v_cmp_ngt_f32_e32 vcc, s1, v10
	global_load_dword v0, v[0:1], off
	s_waitcnt vmcnt(0)
	v_mul_f32_e32 v1, v2, v0
	ds_bpermute_b32 v1, v6, v1
	s_waitcnt lgkmcnt(0)
	v_fmac_f32_e32 v1, v2, v0
	ds_bpermute_b32 v0, v4, v1
	s_waitcnt lgkmcnt(0)
	v_add_f32_e32 v0, v1, v0
	ds_bpermute_b32 v1, v7, v0
	s_waitcnt lgkmcnt(0)
	v_add_f32_e32 v0, v0, v1
	ds_bpermute_b32 v1, v8, v0
	s_waitcnt lgkmcnt(0)
	v_add_f32_e32 v0, v0, v1
	ds_bpermute_b32 v1, v9, v0
	s_waitcnt lgkmcnt(0)
	v_add_f32_e32 v0, v0, v1
	ds_bpermute_b32 v1, v5, v0
	s_waitcnt lgkmcnt(0)
	v_add_f32_e32 v0, v0, v1
	v_mul_f32_e32 v1, 0x3fb8aa3b, v10
	v_fma_f32 v2, v10, s0, -v1
	v_rndne_f32_e32 v3, v1
	v_fmac_f32_e32 v2, 0x32a5705f, v10
	v_sub_f32_e32 v1, v1, v3
	v_add_f32_e32 v1, v1, v2
	v_exp_f32_e32 v1, v1
	v_cvt_i32_f32_e32 v2, v3
	v_ldexp_f32 v1, v1, v2
	v_mul_f32_e32 v2, 0x3fb8aa3b, v0
	v_fma_f32 v3, v0, s0, -v2
	v_rndne_f32_e32 v4, v2
	v_fmac_f32_e32 v3, 0x32a5705f, v0
	v_sub_f32_e32 v2, v2, v4
	v_add_f32_e32 v2, v2, v3
	v_exp_f32_e32 v2, v2
	v_cvt_i32_f32_e32 v3, v4
	v_cndmask_b32_e32 v1, 0, v1, vcc
	v_cmp_nlt_f32_e32 vcc, s4, v10
	s_sub_i32 s0, s74, s71
	v_ldexp_f32 v2, v2, v3
	v_cndmask_b32_e32 v1, v210, v1, vcc
	v_cmp_ngt_f32_e32 vcc, s1, v0
	v_readlane_b32 s1, v249, 2
	s_add_i32 s96, s0, s1
	v_cndmask_b32_e32 v2, 0, v2, vcc
	v_cmp_nlt_f32_e32 vcc, s4, v0
	s_cmpk_gt_i32 s96, 0x7ff
	s_nop 0
	v_cndmask_b32_e32 v0, v210, v2, vcc
	v_sub_f32_e32 v0, v1, v0
	v_add_f32_e32 v0, v222, v0
	s_nop 0
	v_readfirstlane_b32 s75, v0
	s_cbranch_scc1 .LBB0_241
	s_lshl_b32 s0, s74, 7
	s_ashr_i32 s1, s0, 31
	s_lshl_b64 s[0:1], s[0:1], 2
	s_add_u32 s38, s44, s0
	s_addc_u32 s39, s45, s1
	s_add_i32 s12, s74, s70
	s_lshl_b32 s72, s12, 7
	s_mov_b32 s73, s96
	v_lshlrev_b32_e32 v255, 4, v204
	v_add_u32_e32 v255, 0x1b000, v255
	ds_write_b128 v255, v[156:159]
	ds_write_b128 v255, v[160:163] offset:8192
	ds_write_b128 v255, v[214:217] offset:20736
	ds_write_b128 v255, v[218:221] offset:28928
	s_waitcnt lgkmcnt(0)
	s_branch .LBB0_151

; #define LAS __attribute__((address_space(3)))
; __device__ __forceinline__ void da_unit(LAS unsigned char* lds, const bf16_t* __restrict__ proj, bf16_t* __restrict__ y, int unit,
;                                         const float* __restrict__ t5, float lam, float one_m_li, const float* __restrict__ subg) {
;     ...
;     const int bh = unit >> 5, qb = unit & 31, b = bh >> 2, h = bh & 3;
;     const size_t rowbase = (size_t)b * 4096;
;     const int qblk = qb * 128, q0 = qblk + qg * 32, q = q0 + l31;
;     LAS float* tbl = (LAS float*)(lds + DA_TBL_OFF);
;     __syncthreads();
;     if (tid < 257) { const int rel = tid - 128, a = rel < 0 ? -rel : rel; int large = 8 + (31 - __builtin_clz((unsigned)(a * a) | 1u)) - 6; large = large > 15 ? 15 : large;
;         const int bucket = (rel > 0 ? 16 : 0) + (a < 8 ? a : large); tbl[tid] = t5[bucket * 4 + h] * LOG2E; }
;     LAS float* sgt = (LAS float*)(lds + DA_TBL_OFF + 2048);
;     if (tid >= 384) sgt[tid - 384] = subg[tid - 384];
;     { const float bl_ = t5[15 * 4 + h], br_ = t5[31 * 4 + h];
; #pragma unroll
;       for (int k_ = 0; k_ < 3; ++k_) { const int e_ = tid + 512 * k_;
;           if (e_ < 2 * 641) { const int side = e_ >= 641 ? 1 : 0, rel0 = e_ - 641 * side - 320, rel = clampi(rel0, -128, 128), a = rel < 0 ? -rel : rel;
;               int large = 8 + (31 - __builtin_clz((unsigned)(a * a) | 1u)) - 6; large = large > 15 ? 15 : large;
;               const int bucket = (rel > 0 ? 16 : 0) + (a < 8 ? a : large);
;               ((LAS float*)(lds + DA_DL_OFF))[e_ + (side ? (DA_DR_OFF - DA_DL_OFF) / 4 - 641 : 0)] = (t5[bucket * 4 + h] - (side ? br_ : bl_)) * (LOG2E / QK_C); } } }
.LBB0_151:
	s_nop 2
	v_mov_b32_e32 v0, v204
	s_movk_i32 s4, 0x101
	v_readfirstlane_b32 s0, v222
	s_bfe_u32 s9, s73, 0x20005
	v_readfirstlane_b32 s1, v0
	v_cmp_gt_i32_e32 vcc, s4, v0
	s_barrier
	s_cmp_eq_u32 s9, s101
	s_mov_b32 s101, s9
	s_cbranch_scc1 .LBB0_161
	s_and_saveexec_b64 s[30:31], vcc
	s_cbranch_execz .LBB0_153
	v_add_u32_e32 v1, 0xffffff80, v0
	v_sub_u32_e32 v2, 0x80, v0
	v_cmp_gt_i32_e32 vcc, s35, v0
	s_nop 1
	v_cndmask_b32_e32 v1, v1, v2, vcc
	v_mul_lo_u32 v2, v1, v1
	v_or_b32_e32 v2, 1, v2
	v_ffbh_u32_e32 v2, v2
	v_sub_u32_e32 v2, 33, v2
	v_cmp_lt_i32_e32 vcc, s35, v0
	v_min_u32_e32 v2, 15, v2
	s_nop 0
	v_cndmask_b32_e64 v3, 0, 16, vcc
	v_cmp_gt_i32_e32 vcc, 8, v1
	s_nop 1
	v_cndmask_b32_e32 v1, v2, v1, vcc
	v_add_u32_e32 v1, v1, v3
	v_lshl_or_b32 v2, v1, 2, s9
	v_ashrrev_i32_e32 v3, 31, v2
	v_lshl_add_u64 v[2:3], v[2:3], 2, s[46:47]
	global_load_dword v1, v[2:3], off
	v_lshl_add_u32 v2, v0, 2, 0
	v_add_u32_e32 v2, 0x18c00, v2
	s_waitcnt vmcnt(0)
	v_mul_f32_e32 v1, 0x3fb8aa3b, v1
	ds_write_b32 v2, v1
